# speedup vs baseline: 1.0292x; 1.0049x over previous
; __device__ __forceinline__ unsigned cvt_pk_bf16(float lo, float hi) { unsigned r; asm volatile("v_cvt_pk_bf16_f32 %0, %1, %2" : "=v"(r) : "v"(lo), "v"(hi)); return r; }
; #define GAS __attribute__((address_space(1)))
;     __device__ __forceinline__ void operator()(const f32x4 (&acc)[2][2][4][2], const Unit& u, int wr, int wc, int fr, int fq) const {
;     ...
;             for (int m = 0; m < 4; ++m) {
;                 const int row = row0 + ai * 128 + m * 16;
;                 const float rs = rsl[u.ord * 256 + wr * 64 + fr + ai * 128 + m * 16];
;                 float o[8];
; #pragma unroll
;                 for (int n = 0; n < 2; ++n)
; #pragma unroll
;                     for (int i = 0; i < 4; ++i) {
;                         const float g = acc[ai][0][m][n][i] * rs, up = acc[ai][1][m][n][i] * rs;
;                         const float e = __builtin_amdgcn_exp2f(-g * 1.4426950408889634f);
;                         o[n * 4 + i] = g * __builtin_amdgcn_rcpf(1.0f + e) * up;
;                     }
;                 u32x4 w; w.x = cvt_pk_bf16(o[0], o[1]); w.y = cvt_pk_bf16(o[2], o[3]); w.z = cvt_pk_bf16(o[4], o[5]); w.w = cvt_pk_bf16(o[6], o[7]);
;                 *(GAS u32x4*)(act + (size_t)row * DFF + col0) = w;
.LBB0_171:
	s_cmpk_lt_u32 s41, 0x80
	s_cselect_b32 s0, s97, s11
	s_cselect_b32 s1, s61, s10
	v_lshl_or_b32 v146, s40, 7, v143
	v_mov_b32_e32 v138, s1
	v_mov_b32_e32 v139, s0
	v_ashrrev_i32_e32 v147, 31, v146
	v_lshl_add_u64 v[138:139], v[146:147], 1, v[138:139]
	v_lshl_add_u32 v146, s57, 10, v142
	ds_read_b32 v152, v146
	ds_read_b32 v153, v146 offset:64
	ds_read_b32 v154, v146 offset:128
	ds_read_b32 v155, v146 offset:192
	ds_read_b32 v156, v146 offset:512
	ds_read_b32 v157, v146 offset:576
	ds_read_b32 v158, v146 offset:640
	ds_read_b32 v159, v146 offset:704
	s_lshl_b32 s0, s41, 8
	s_and_b32 s0, s0, 0x7f00
	v_add_u32_e32 v145, s0, v140
	s_andn2_b64 vcc, exec, s[6:7]
	s_waitcnt lgkmcnt(0)
	v_mul_f32_e32 v190, 0xbfb8aa3b, v152
	v_mul_f32_e32 v191, v152, v152
	v_rcp_f32_e32 v191, v191
	v_mul_f32_e32 v168, v124, v190
	v_mul_f32_e32 v169, v125, v190
	v_mul_f32_e32 v170, v126, v190
	v_mul_f32_e32 v171, v127, v190
	v_mul_f32_e32 v172, v116, v190
	v_mul_f32_e32 v173, v117, v190
	v_mul_f32_e32 v174, v118, v190
	v_mul_f32_e32 v175, v119, v190
	v_exp_f32_e32 v168, v168
	v_exp_f32_e32 v169, v169
	v_exp_f32_e32 v170, v170
	v_exp_f32_e32 v171, v171
	v_exp_f32_e32 v172, v172
	v_exp_f32_e32 v173, v173
	v_exp_f32_e32 v174, v174
	v_exp_f32_e32 v175, v175
	v_mul_f32_e32 v120, v124, v120
	v_mul_f32_e32 v121, v125, v121
	v_mul_f32_e32 v122, v126, v122
	v_mul_f32_e32 v123, v127, v123
	v_mul_f32_e32 v112, v116, v112
	v_mul_f32_e32 v113, v117, v113
	v_mul_f32_e32 v114, v118, v114
	v_mul_f32_e32 v115, v119, v115
	v_fma_f32 v168, v168, v191, v191
	v_fma_f32 v169, v169, v191, v191
	v_fma_f32 v170, v170, v191, v191
	v_fma_f32 v171, v171, v191, v191
	v_fma_f32 v172, v172, v191, v191
	v_fma_f32 v173, v173, v191, v191
	v_fma_f32 v174, v174, v191, v191
	v_fma_f32 v175, v175, v191, v191
	v_rcp_f32_e32 v168, v168
	v_rcp_f32_e32 v169, v169
	v_rcp_f32_e32 v170, v170
	v_rcp_f32_e32 v171, v171
	v_rcp_f32_e32 v172, v172
	v_rcp_f32_e32 v173, v173
	v_rcp_f32_e32 v174, v174
	v_rcp_f32_e32 v175, v175
	v_mul_f32_e32 v120, v120, v168
	v_mul_f32_e32 v121, v121, v169
	v_mul_f32_e32 v122, v122, v170
	v_mul_f32_e32 v123, v123, v171
	v_mul_f32_e32 v112, v112, v172
	v_mul_f32_e32 v113, v113, v173
	v_mul_f32_e32 v114, v114, v174
	v_mul_f32_e32 v115, v115, v175
	v_cvt_pk_bf16_f32 v176, v120, v121
	v_cvt_pk_bf16_f32 v177, v122, v123
	v_cvt_pk_bf16_f32 v178, v112, v113
	v_cvt_pk_bf16_f32 v179, v114, v115
	v_mad_i64_i32 v[180:181], s[38:39], v145, s53, v[138:139]
	global_store_dwordx4 v[180:181], v[176:179], off
	v_mul_f32_e32 v190, 0xbfb8aa3b, v153
	v_mul_f32_e32 v191, v153, v153
	v_rcp_f32_e32 v191, v191
	v_mul_f32_e32 v168, v108, v190
	v_mul_f32_e32 v169, v109, v190
	v_mul_f32_e32 v170, v110, v190
	v_mul_f32_e32 v171, v111, v190
	v_mul_f32_e32 v172, v100, v190
	v_mul_f32_e32 v173, v101, v190
	v_mul_f32_e32 v174, v102, v190
	v_mul_f32_e32 v175, v103, v190
	v_exp_f32_e32 v168, v168
	v_exp_f32_e32 v169, v169
	v_exp_f32_e32 v170, v170
	v_exp_f32_e32 v171, v171
	v_exp_f32_e32 v172, v172
	v_exp_f32_e32 v173, v173
	v_exp_f32_e32 v174, v174
	v_exp_f32_e32 v175, v175
	v_mul_f32_e32 v104, v108, v104
	v_mul_f32_e32 v105, v109, v105
	v_mul_f32_e32 v106, v110, v106
	v_mul_f32_e32 v107, v111, v107
	v_mul_f32_e32 v96, v100, v96
	v_mul_f32_e32 v97, v101, v97
	v_mul_f32_e32 v98, v102, v98
	v_mul_f32_e32 v99, v103, v99
	v_fma_f32 v168, v168, v191, v191
	v_fma_f32 v169, v169, v191, v191
	v_fma_f32 v170, v170, v191, v191
	v_fma_f32 v171, v171, v191, v191
	v_fma_f32 v172, v172, v191, v191
	v_fma_f32 v173, v173, v191, v191
	v_fma_f32 v174, v174, v191, v191
	v_fma_f32 v175, v175, v191, v191
	v_rcp_f32_e32 v168, v168
	v_rcp_f32_e32 v169, v169
	v_rcp_f32_e32 v170, v170
	v_rcp_f32_e32 v171, v171
	v_rcp_f32_e32 v172, v172
	v_rcp_f32_e32 v173, v173
	v_rcp_f32_e32 v174, v174
	v_rcp_f32_e32 v175, v175
	v_mul_f32_e32 v104, v104, v168
	v_mul_f32_e32 v105, v105, v169
	v_mul_f32_e32 v106, v106, v170
	v_mul_f32_e32 v107, v107, v171
	v_mul_f32_e32 v96, v96, v172
	v_mul_f32_e32 v97, v97, v173
	v_mul_f32_e32 v98, v98, v174
	v_mul_f32_e32 v99, v99, v175
	v_cvt_pk_bf16_f32 v184, v104, v105
	v_cvt_pk_bf16_f32 v185, v106, v107
	v_cvt_pk_bf16_f32 v186, v96, v97
	v_cvt_pk_bf16_f32 v187, v98, v99
	v_add_u32_e32 v182, 16, v145
	v_mad_i64_i32 v[188:189], s[38:39], v182, s53, v[138:139]
	global_store_dwordx4 v[188:189], v[184:187], off
	v_mul_f32_e32 v190, 0xbfb8aa3b, v154
	v_mul_f32_e32 v191, v154, v154
	v_rcp_f32_e32 v191, v191
	v_mul_f32_e32 v168, v92, v190
	v_mul_f32_e32 v169, v93, v190
	v_mul_f32_e32 v170, v94, v190
	v_mul_f32_e32 v171, v95, v190
	v_mul_f32_e32 v172, v84, v190
	v_mul_f32_e32 v173, v85, v190
	v_mul_f32_e32 v174, v86, v190
	v_mul_f32_e32 v175, v87, v190
	v_exp_f32_e32 v168, v168
	v_exp_f32_e32 v169, v169
	v_exp_f32_e32 v170, v170
	v_exp_f32_e32 v171, v171
	v_exp_f32_e32 v172, v172
	v_exp_f32_e32 v173, v173
	v_exp_f32_e32 v174, v174
	v_exp_f32_e32 v175, v175
	v_mul_f32_e32 v88, v92, v88
	v_mul_f32_e32 v89, v93, v89
	v_mul_f32_e32 v90, v94, v90
	v_mul_f32_e32 v91, v95, v91
	v_mul_f32_e32 v80, v84, v80
	v_mul_f32_e32 v81, v85, v81
	v_mul_f32_e32 v82, v86, v82
	v_mul_f32_e32 v83, v87, v83
	v_fma_f32 v168, v168, v191, v191
	v_fma_f32 v169, v169, v191, v191
	v_fma_f32 v170, v170, v191, v191
	v_fma_f32 v171, v171, v191, v191
	v_fma_f32 v172, v172, v191, v191
	v_fma_f32 v173, v173, v191, v191
	v_fma_f32 v174, v174, v191, v191
	v_fma_f32 v175, v175, v191, v191
	v_rcp_f32_e32 v168, v168
	v_rcp_f32_e32 v169, v169
	v_rcp_f32_e32 v170, v170
	v_rcp_f32_e32 v171, v171
	v_rcp_f32_e32 v172, v172
	v_rcp_f32_e32 v173, v173
	v_rcp_f32_e32 v174, v174
	v_rcp_f32_e32 v175, v175
	v_mul_f32_e32 v88, v88, v168
	v_mul_f32_e32 v89, v89, v169
; __device__ __forceinline__ unsigned cvt_pk_bf16(float lo, float hi) { unsigned r; asm volatile("v_cvt_pk_bf16_f32 %0, %1, %2" : "=v"(r) : "v"(lo), "v"(hi)); return r; }
; #define GAS __attribute__((address_space(1)))
;     __device__ __forceinline__ void operator()(const f32x4 (&acc)[2][2][4][2], const Unit& u, int wr, int wc, int fr, int fq) const {
;     ...
;             for (int m = 0; m < 4; ++m) {
;                 const int row = row0 + ai * 128 + m * 16;
;                 const float rs = rsl[u.ord * 256 + wr * 64 + fr + ai * 128 + m * 16];
;                 float o[8];
; #pragma unroll
;                 for (int n = 0; n < 2; ++n)
; #pragma unroll
;                     for (int i = 0; i < 4; ++i) {
;                         const float g = acc[ai][0][m][n][i] * rs, up = acc[ai][1][m][n][i] * rs;
;                         const float e = __builtin_amdgcn_exp2f(-g * 1.4426950408889634f);
;                         o[n * 4 + i] = g * __builtin_amdgcn_rcpf(1.0f + e) * up;
;                     }
;                 u32x4 w; w.x = cvt_pk_bf16(o[0], o[1]); w.y = cvt_pk_bf16(o[2], o[3]); w.z = cvt_pk_bf16(o[4], o[5]); w.w = cvt_pk_bf16(o[6], o[7]);
;                 *(GAS u32x4*)(act + (size_t)row * DFF + col0) = w;
;             }
	v_mul_f32_e32 v90, v90, v170
	v_mul_f32_e32 v91, v91, v171
	v_mul_f32_e32 v80, v80, v172
	v_mul_f32_e32 v81, v81, v173
	v_mul_f32_e32 v82, v82, v174
	v_mul_f32_e32 v83, v83, v175
	v_cvt_pk_bf16_f32 v176, v88, v89
	v_cvt_pk_bf16_f32 v177, v90, v91
	v_cvt_pk_bf16_f32 v178, v80, v81
	v_cvt_pk_bf16_f32 v179, v82, v83
	v_add_u32_e32 v182, 32, v145
	v_mad_i64_i32 v[180:181], s[38:39], v182, s53, v[138:139]
	global_store_dwordx4 v[180:181], v[176:179], off
	v_mul_f32_e32 v190, 0xbfb8aa3b, v155
	v_mul_f32_e32 v191, v155, v155
	v_rcp_f32_e32 v191, v191
	v_mul_f32_e32 v168, v76, v190
	v_mul_f32_e32 v169, v77, v190
	v_mul_f32_e32 v170, v78, v190
	v_mul_f32_e32 v171, v79, v190
	v_mul_f32_e32 v172, v68, v190
	v_mul_f32_e32 v173, v69, v190
	v_mul_f32_e32 v174, v70, v190
	v_mul_f32_e32 v175, v71, v190
	v_exp_f32_e32 v168, v168
	v_exp_f32_e32 v169, v169
	v_exp_f32_e32 v170, v170
	v_exp_f32_e32 v171, v171
	v_exp_f32_e32 v172, v172
	v_exp_f32_e32 v173, v173
	v_exp_f32_e32 v174, v174
	v_exp_f32_e32 v175, v175
	v_mul_f32_e32 v72, v76, v72
	v_mul_f32_e32 v73, v77, v73
	v_mul_f32_e32 v74, v78, v74
	v_mul_f32_e32 v75, v79, v75
	v_mul_f32_e32 v64, v68, v64
	v_mul_f32_e32 v65, v69, v65
	v_mul_f32_e32 v66, v70, v66
	v_mul_f32_e32 v67, v71, v67
	v_fma_f32 v168, v168, v191, v191
	v_fma_f32 v169, v169, v191, v191
	v_fma_f32 v170, v170, v191, v191
	v_fma_f32 v171, v171, v191, v191
	v_fma_f32 v172, v172, v191, v191
	v_fma_f32 v173, v173, v191, v191
	v_fma_f32 v174, v174, v191, v191
	v_fma_f32 v175, v175, v191, v191
	v_rcp_f32_e32 v168, v168
	v_rcp_f32_e32 v169, v169
	v_rcp_f32_e32 v170, v170
	v_rcp_f32_e32 v171, v171
	v_rcp_f32_e32 v172, v172
	v_rcp_f32_e32 v173, v173
	v_rcp_f32_e32 v174, v174
	v_rcp_f32_e32 v175, v175
	v_mul_f32_e32 v72, v72, v168
	v_mul_f32_e32 v73, v73, v169
	v_mul_f32_e32 v74, v74, v170
	v_mul_f32_e32 v75, v75, v171
	v_mul_f32_e32 v64, v64, v172
	v_mul_f32_e32 v65, v65, v173
	v_mul_f32_e32 v66, v66, v174
	v_mul_f32_e32 v67, v67, v175
	v_cvt_pk_bf16_f32 v184, v72, v73
	v_cvt_pk_bf16_f32 v185, v74, v75
	v_cvt_pk_bf16_f32 v186, v64, v65
	v_cvt_pk_bf16_f32 v187, v66, v67
	v_add_u32_e32 v182, 48, v145
	v_mad_i64_i32 v[188:189], s[38:39], v182, s53, v[138:139]
	global_store_dwordx4 v[188:189], v[184:187], off
	v_mul_f32_e32 v190, 0xbfb8aa3b, v156
	v_mul_f32_e32 v191, v156, v156
	v_rcp_f32_e32 v191, v191
	v_mul_f32_e32 v168, v60, v190
	v_mul_f32_e32 v169, v61, v190
	v_mul_f32_e32 v170, v62, v190
	v_mul_f32_e32 v171, v63, v190
	v_mul_f32_e32 v172, v52, v190
	v_mul_f32_e32 v173, v53, v190
	v_mul_f32_e32 v174, v54, v190
	v_mul_f32_e32 v175, v55, v190
	v_exp_f32_e32 v168, v168
	v_exp_f32_e32 v169, v169
	v_exp_f32_e32 v170, v170
	v_exp_f32_e32 v171, v171
	v_exp_f32_e32 v172, v172
	v_exp_f32_e32 v173, v173
	v_exp_f32_e32 v174, v174
	v_exp_f32_e32 v175, v175
	v_mul_f32_e32 v56, v60, v56
	v_mul_f32_e32 v57, v61, v57
	v_mul_f32_e32 v58, v62, v58
	v_mul_f32_e32 v59, v63, v59
	v_mul_f32_e32 v48, v52, v48
	v_mul_f32_e32 v49, v53, v49
	v_mul_f32_e32 v50, v54, v50
	v_mul_f32_e32 v51, v55, v51
	v_fma_f32 v168, v168, v191, v191
	v_fma_f32 v169, v169, v191, v191
	v_fma_f32 v170, v170, v191, v191
	v_fma_f32 v171, v171, v191, v191
	v_fma_f32 v172, v172, v191, v191
	v_fma_f32 v173, v173, v191, v191
	v_fma_f32 v174, v174, v191, v191
	v_fma_f32 v175, v175, v191, v191
	v_rcp_f32_e32 v168, v168
	v_rcp_f32_e32 v169, v169
	v_rcp_f32_e32 v170, v170
	v_rcp_f32_e32 v171, v171
	v_rcp_f32_e32 v172, v172
	v_rcp_f32_e32 v173, v173
	v_rcp_f32_e32 v174, v174
	v_rcp_f32_e32 v175, v175
	v_mul_f32_e32 v56, v56, v168
	v_mul_f32_e32 v57, v57, v169
	v_mul_f32_e32 v58, v58, v170
	v_mul_f32_e32 v59, v59, v171
	v_mul_f32_e32 v48, v48, v172
	v_mul_f32_e32 v49, v49, v173
	v_mul_f32_e32 v50, v50, v174
	v_mul_f32_e32 v51, v51, v175
	v_cvt_pk_bf16_f32 v176, v56, v57
	v_cvt_pk_bf16_f32 v177, v58, v59
	v_cvt_pk_bf16_f32 v178, v48, v49
	v_cvt_pk_bf16_f32 v179, v50, v51
	v_add_u32_e32 v182, 0x80, v145
	v_mad_i64_i32 v[180:181], s[38:39], v182, s53, v[138:139]
	global_store_dwordx4 v[180:181], v[176:179], off
	v_mul_f32_e32 v190, 0xbfb8aa3b, v157
	v_mul_f32_e32 v191, v157, v157
	v_rcp_f32_e32 v191, v191
	v_mul_f32_e32 v168, v44, v190
	v_mul_f32_e32 v169, v45, v190
	v_mul_f32_e32 v170, v46, v190
	v_mul_f32_e32 v171, v47, v190
	v_mul_f32_e32 v172, v36, v190
	v_mul_f32_e32 v173, v37, v190
	v_mul_f32_e32 v174, v38, v190
	v_mul_f32_e32 v175, v39, v190
	v_exp_f32_e32 v168, v168
	v_exp_f32_e32 v169, v169
	v_exp_f32_e32 v170, v170
	v_exp_f32_e32 v171, v171
	v_exp_f32_e32 v172, v172
	v_exp_f32_e32 v173, v173
	v_exp_f32_e32 v174, v174
	v_exp_f32_e32 v175, v175
	v_mul_f32_e32 v40, v44, v40
	v_mul_f32_e32 v41, v45, v41
	v_mul_f32_e32 v42, v46, v42
	v_mul_f32_e32 v43, v47, v43
	v_mul_f32_e32 v32, v36, v32
	v_mul_f32_e32 v33, v37, v33
; __device__ __forceinline__ unsigned cvt_pk_bf16(float lo, float hi) { unsigned r; asm volatile("v_cvt_pk_bf16_f32 %0, %1, %2" : "=v"(r) : "v"(lo), "v"(hi)); return r; }
; #define GAS __attribute__((address_space(1)))
;     __device__ __forceinline__ void operator()(const f32x4 (&acc)[2][2][4][2], const Unit& u, int wr, int wc, int fr, int fq) const {
;     ...
;             for (int m = 0; m < 4; ++m) {
;                 const int row = row0 + ai * 128 + m * 16;
;                 const float rs = rsl[u.ord * 256 + wr * 64 + fr + ai * 128 + m * 16];
;                 float o[8];
; #pragma unroll
;                 for (int n = 0; n < 2; ++n)
; #pragma unroll
;                     for (int i = 0; i < 4; ++i) {
;                         const float g = acc[ai][0][m][n][i] * rs, up = acc[ai][1][m][n][i] * rs;
;                         const float e = __builtin_amdgcn_exp2f(-g * 1.4426950408889634f);
;                         o[n * 4 + i] = g * __builtin_amdgcn_rcpf(1.0f + e) * up;
;                     }
;                 u32x4 w; w.x = cvt_pk_bf16(o[0], o[1]); w.y = cvt_pk_bf16(o[2], o[3]); w.z = cvt_pk_bf16(o[4], o[5]); w.w = cvt_pk_bf16(o[6], o[7]);
;                 *(GAS u32x4*)(act + (size_t)row * DFF + col0) = w;
;             }
	v_mul_f32_e32 v34, v38, v34
	v_mul_f32_e32 v35, v39, v35
	v_fma_f32 v168, v168, v191, v191
	v_fma_f32 v169, v169, v191, v191
	v_fma_f32 v170, v170, v191, v191
	v_fma_f32 v171, v171, v191, v191
	v_fma_f32 v172, v172, v191, v191
	v_fma_f32 v173, v173, v191, v191
	v_fma_f32 v174, v174, v191, v191
	v_fma_f32 v175, v175, v191, v191
	v_rcp_f32_e32 v168, v168
	v_rcp_f32_e32 v169, v169
	v_rcp_f32_e32 v170, v170
	v_rcp_f32_e32 v171, v171
	v_rcp_f32_e32 v172, v172
	v_rcp_f32_e32 v173, v173
	v_rcp_f32_e32 v174, v174
	v_rcp_f32_e32 v175, v175
	v_mul_f32_e32 v40, v40, v168
	v_mul_f32_e32 v41, v41, v169
	v_mul_f32_e32 v42, v42, v170
	v_mul_f32_e32 v43, v43, v171
	v_mul_f32_e32 v32, v32, v172
	v_mul_f32_e32 v33, v33, v173
	v_mul_f32_e32 v34, v34, v174
	v_mul_f32_e32 v35, v35, v175
	v_cvt_pk_bf16_f32 v184, v40, v41
	v_cvt_pk_bf16_f32 v185, v42, v43
	v_cvt_pk_bf16_f32 v186, v32, v33
	v_cvt_pk_bf16_f32 v187, v34, v35
	v_add_u32_e32 v182, 0x90, v145
	v_mad_i64_i32 v[188:189], s[38:39], v182, s53, v[138:139]
	global_store_dwordx4 v[188:189], v[184:187], off
	v_mul_f32_e32 v190, 0xbfb8aa3b, v158
	v_mul_f32_e32 v191, v158, v158
	v_rcp_f32_e32 v191, v191
	v_mul_f32_e32 v168, v28, v190
	v_mul_f32_e32 v169, v29, v190
	v_mul_f32_e32 v170, v30, v190
	v_mul_f32_e32 v171, v31, v190
	v_mul_f32_e32 v172, v20, v190
	v_mul_f32_e32 v173, v21, v190
	v_mul_f32_e32 v174, v22, v190
	v_mul_f32_e32 v175, v23, v190
	v_exp_f32_e32 v168, v168
	v_exp_f32_e32 v169, v169
	v_exp_f32_e32 v170, v170
	v_exp_f32_e32 v171, v171
	v_exp_f32_e32 v172, v172
	v_exp_f32_e32 v173, v173
	v_exp_f32_e32 v174, v174
	v_exp_f32_e32 v175, v175
	v_mul_f32_e32 v24, v28, v24
	v_mul_f32_e32 v25, v29, v25
	v_mul_f32_e32 v26, v30, v26
	v_mul_f32_e32 v27, v31, v27
	v_mul_f32_e32 v16, v20, v16
	v_mul_f32_e32 v17, v21, v17
	v_mul_f32_e32 v18, v22, v18
	v_mul_f32_e32 v19, v23, v19
	v_fma_f32 v168, v168, v191, v191
	v_fma_f32 v169, v169, v191, v191
	v_fma_f32 v170, v170, v191, v191
	v_fma_f32 v171, v171, v191, v191
	v_fma_f32 v172, v172, v191, v191
	v_fma_f32 v173, v173, v191, v191
	v_fma_f32 v174, v174, v191, v191
	v_fma_f32 v175, v175, v191, v191
	v_rcp_f32_e32 v168, v168
	v_rcp_f32_e32 v169, v169
	v_rcp_f32_e32 v170, v170
	v_rcp_f32_e32 v171, v171
	v_rcp_f32_e32 v172, v172
	v_rcp_f32_e32 v173, v173
	v_rcp_f32_e32 v174, v174
	v_rcp_f32_e32 v175, v175
	v_mul_f32_e32 v24, v24, v168
	v_mul_f32_e32 v25, v25, v169
	v_mul_f32_e32 v26, v26, v170
	v_mul_f32_e32 v27, v27, v171
	v_mul_f32_e32 v16, v16, v172
	v_mul_f32_e32 v17, v17, v173
	v_mul_f32_e32 v18, v18, v174
	v_mul_f32_e32 v19, v19, v175
	v_cvt_pk_bf16_f32 v176, v24, v25
	v_cvt_pk_bf16_f32 v177, v26, v27
	v_cvt_pk_bf16_f32 v178, v16, v17
	v_cvt_pk_bf16_f32 v179, v18, v19
	v_add_u32_e32 v182, 0xa0, v145
	v_mad_i64_i32 v[180:181], s[38:39], v182, s53, v[138:139]
	global_store_dwordx4 v[180:181], v[176:179], off
	v_mul_f32_e32 v190, 0xbfb8aa3b, v159
	v_mul_f32_e32 v191, v159, v159
	v_rcp_f32_e32 v191, v191
	v_mul_f32_e32 v168, v12, v190
	v_mul_f32_e32 v169, v13, v190
	v_mul_f32_e32 v170, v14, v190
	v_mul_f32_e32 v171, v15, v190
	v_mul_f32_e32 v172, v4, v190
	v_mul_f32_e32 v173, v5, v190
	v_mul_f32_e32 v174, v6, v190
	v_mul_f32_e32 v175, v7, v190
	v_exp_f32_e32 v168, v168
	v_exp_f32_e32 v169, v169
	v_exp_f32_e32 v170, v170
	v_exp_f32_e32 v171, v171
	v_exp_f32_e32 v172, v172
	v_exp_f32_e32 v173, v173
	v_exp_f32_e32 v174, v174
	v_exp_f32_e32 v175, v175
	v_mul_f32_e32 v8, v12, v8
	v_mul_f32_e32 v9, v13, v9
	v_mul_f32_e32 v10, v14, v10
	v_mul_f32_e32 v11, v15, v11
	v_mul_f32_e32 v0, v4, v0
	v_mul_f32_e32 v1, v5, v1
	v_mul_f32_e32 v2, v6, v2
	v_mul_f32_e32 v3, v7, v3
	v_fma_f32 v168, v168, v191, v191
	v_fma_f32 v169, v169, v191, v191
	v_fma_f32 v170, v170, v191, v191
	v_fma_f32 v171, v171, v191, v191
	v_fma_f32 v172, v172, v191, v191
	v_fma_f32 v173, v173, v191, v191
	v_fma_f32 v174, v174, v191, v191
	v_fma_f32 v175, v175, v191, v191
	v_rcp_f32_e32 v168, v168
	v_rcp_f32_e32 v169, v169
	v_rcp_f32_e32 v170, v170
	v_rcp_f32_e32 v171, v171
	v_rcp_f32_e32 v172, v172
	v_rcp_f32_e32 v173, v173
	v_rcp_f32_e32 v174, v174
	v_rcp_f32_e32 v175, v175
	v_mul_f32_e32 v8, v8, v168
	v_mul_f32_e32 v9, v9, v169
	v_mul_f32_e32 v10, v10, v170
	v_mul_f32_e32 v11, v11, v171
	v_mul_f32_e32 v0, v0, v172
	v_mul_f32_e32 v1, v1, v173
	v_mul_f32_e32 v2, v2, v174
	v_mul_f32_e32 v3, v3, v175
	v_cvt_pk_bf16_f32 v184, v8, v9
	v_cvt_pk_bf16_f32 v185, v10, v11
	v_cvt_pk_bf16_f32 v186, v0, v1
	v_cvt_pk_bf16_f32 v187, v2, v3
	v_add_u32_e32 v182, 0xb0, v145
	v_mad_i64_i32 v[188:189], s[38:39], v182, s53, v[138:139]
	global_store_dwordx4 v[188:189], v[184:187], off
	s_mov_b64 s[38:39], -1
	s_cbranch_vccnz .LBB0_164
	s_andn2_b64 vcc, exec, s[18:19]
	s_cbranch_vccnz .LBB0_163
	s_barrier
	s_branch .LBB0_163
